# placement: P8 row pass moved 8 bytes (start at 48 mod 64), PEER placements kept
# speedup vs baseline: 1.0063x; 1.0063x over previous
; __device__ __forceinline__ void xn2_rows(const bf16* __restrict__ hb, const float* __restrict__ g, bf16* __restrict__ outp, unsigned char* __restrict__ xq, float* __restrict__ xs, int gwave, int nwaves, int lane, int rend) {
;     ...
;     for (int row = gwave; row < rend; row += nwaves) {
;         const v4u* xb = (const v4u*)(hb + (size_t)row * D) + lane;
;         float v[2][8]; float ss = 0.f;
; #pragma unroll
;         for (int j = 0; j < 2; ++j) { const v4u w = xb[64 * j]; const unsigned ww[4] = {w.x, w.y, w.z, w.w};
; #pragma unroll
;             for (int e = 0; e < 4; ++e) { v[j][2 * e] = __uint_as_float(ww[e] << 16); v[j][2 * e + 1] = __uint_as_float(ww[e] & 0xffff0000u); ss += v[j][2 * e] * v[j][2 * e] + v[j][2 * e + 1] * v[j][2 * e + 1]; } }
;         ss = wave_sum(ss);
;         const float r = rsqrtf(ss * (1.f / D) + EPS);
;         float y[2][8]; float mx = 0.f;
; #pragma unroll
;         for (int j = 0; j < 2; ++j) { const float4 g0 = ((const float4*)g)[2 * lane + 128 * j], g1 = ((const float4*)g)[2 * lane + 128 * j + 1]; const float gg[8] = {g0.x, g0.y, g0.z, g0.w, g1.x, g1.y, g1.z, g1.w};
; #pragma unroll
;             for (int e = 0; e < 8; ++e) { y[j][e] = v[j][e] * r * gg[e]; mx = fmaxf(mx, fabsf(y[j][e])); }
;             v4u ow; ow.x = pk2(y[j][0], y[j][1]); ow.y = pk2(y[j][2], y[j][3]); ow.z = pk2(y[j][4], y[j][5]); ow.w = pk2(y[j][6], y[j][7]);
;             __builtin_amdgcn_raw_buffer_store_b128(ow, rsO, (int)(((unsigned)row * D + 8u * (unsigned)lane + 512u * j) * 2u), 0, 16); }
;         mx = wave_max_dpp(mx);
;         const float sc = mx > 0.f ? mx * (1.f / 119.f) : 1.f, inv = 1.f / sc;
.LBB0_564:
	s_or_b64 exec, exec, s[10:11]
	s_andn2_b64 vcc, exec, s[20:21]
	s_barrier
	s_cbranch_vccnz .LBB0_569
	s_nop 0
	s_nop 0
	global_load_dwordx4 v[2:5], v[20:21], off offset:16
	global_load_dwordx4 v[6:9], v[20:21], off
	global_load_dwordx4 v[10:13], v[20:21], off offset:2064
	global_load_dwordx4 v[14:17], v[20:21], off offset:2048
	s_lshl_b32 s10, s42, 6
	s_lshl_b32 s11, s43, 8
	s_add_i32 s24, s10, s11
	s_add_i32 s24, s24, s95
	s_ashr_i32 s25, s24, 31
	s_lshl_b64 s[10:11], s[24:25], 2
	s_lshl_b32 s98, s95, 2
	v_lshl_add_u32 v33, s24, 9, v1
	s_lshl_b64 s[24:25], s[24:25], 11
	v_mov_b32_e32 v27, s25
	v_or_b32_e32 v26, s24, v18
	v_lshl_add_u64 v[148:149], s[90:91], 0, v[26:27]
	s_mov_b32 s24, 0xa400000
	s_mov_b32 s25, 0
	s_nop 0
	v_lshl_add_u64 v[148:149], v[148:149], 0, s[24:25]
	v_lshl_add_u64 v[150:151], v[148:149], 0, s[22:23]
	global_load_dwordx4 v[84:87], v[148:149], off
	global_load_dwordx4 v[88:91], v[148:149], off offset:1024
	global_load_dwordx4 v[92:95], v[150:151], off
	global_load_dwordx4 v[96:99], v[150:151], off offset:1024
	s_mov_b32 s46, 0x4b400008
	s_mov_b32 s47, 0x4b400008
	s_mov_b32 s48, 0x0c0c0400
	s_mov_b32 s49, 0x05040100
	s_mov_b32 s45, 0x0f0f0f0f
	s_mov_b32 s100, 0x8000
	s_mov_b32 s101, 0
	s_mov_b32 s32, 0
	v_mov_b32_e32 v55, 0
	v_mov_b32_e32 v61, 0
	v_mov_b32_e32 v210, v26
	v_mov_b32_e32 v211, v33
	s_waitcnt vmcnt(0)

; #define LAS __attribute__((address_space(3)))
; __global__ void __launch_bounds__(NTHR, 2) k_main(Args a) {
;     ...
;             for (int i = tid; i < 2 * 128 * 8; i += NTHR) {
;                 const int pc = i & 7, key = (i >> 3) & 127, hf = (i >> 10) & 1, hl = i >> 11;
;                 *(LAS v4u*)(KHL + ((hl * 2 + hf) * 128 + key) * 72 + pc * 8) = *(const v4u*)((hl ? KL : KH) + (size_t)(hf * 128 + key) * 64 + pc * 8);
;             }
;             __syncthreads();
.LBB0_665:
	v_mov_b32_e32 v20, s53
	v_mov_b32_e32 v21, s49
	v_mov_b32_e32 v22, s52
	v_mov_b32_e32 v23, s48
	v_lshlrev_b32_e32 v24, 4, v19
	v_cmp_gt_u32_e32 vcc, s54, v19
	v_lshlrev_b32_e32 v25, 1, v18
	v_and_b32_e32 v82, 0x7f80, v24
	v_cndmask_b32_e32 v21, v20, v21, vcc
	v_cndmask_b32_e32 v20, v22, v23, vcc
	v_lshl_add_u64 v[20:21], v[20:21], 0, v[82:83]
	v_and_b32_e32 v82, 0x70, v25
	v_lshl_add_u64 v[20:21], v[20:21], 0, v[82:83]
	global_load_dwordx4 v[162:165], v[20:21], off
	v_lshrrev_b32_e32 v24, 3, v19
	v_mul_lo_u32 v24, v24, s56
	v_add3_u32 v178, 0, v24, v82
	v_add_u32_e32 v19, 0x200, v19
	v_add_u32_e32 v18, 0x1000, v18
	v_mov_b32_e32 v20, s53
	v_mov_b32_e32 v21, s49
	v_mov_b32_e32 v22, s52
	v_mov_b32_e32 v23, s48
	v_lshlrev_b32_e32 v24, 4, v19
	v_cmp_gt_u32_e32 vcc, s54, v19
	v_lshlrev_b32_e32 v25, 1, v18
	v_and_b32_e32 v82, 0x7f80, v24
	v_cndmask_b32_e32 v21, v20, v21, vcc
	v_cndmask_b32_e32 v20, v22, v23, vcc
	v_lshl_add_u64 v[20:21], v[20:21], 0, v[82:83]
	v_and_b32_e32 v82, 0x70, v25
	v_lshl_add_u64 v[20:21], v[20:21], 0, v[82:83]
	global_load_dwordx4 v[166:169], v[20:21], off
	v_lshrrev_b32_e32 v24, 3, v19
	v_mul_lo_u32 v24, v24, s56
	v_add3_u32 v179, 0, v24, v82
	v_add_u32_e32 v19, 0x200, v19
	v_add_u32_e32 v18, 0x1000, v18
	v_mov_b32_e32 v20, s53
	v_mov_b32_e32 v21, s49
	v_mov_b32_e32 v22, s52
	v_mov_b32_e32 v23, s48
	v_lshlrev_b32_e32 v24, 4, v19
	v_cmp_gt_u32_e32 vcc, s54, v19
	v_lshlrev_b32_e32 v25, 1, v18
	v_and_b32_e32 v82, 0x7f80, v24
	v_cndmask_b32_e32 v21, v20, v21, vcc
	v_cndmask_b32_e32 v20, v22, v23, vcc
	v_lshl_add_u64 v[20:21], v[20:21], 0, v[82:83]
	v_and_b32_e32 v82, 0x70, v25
	v_lshl_add_u64 v[20:21], v[20:21], 0, v[82:83]
	global_load_dwordx4 v[170:173], v[20:21], off
	v_lshrrev_b32_e32 v24, 3, v19
	v_mul_lo_u32 v24, v24, s56
	v_add3_u32 v180, 0, v24, v82
	v_add_u32_e32 v19, 0x200, v19
	v_add_u32_e32 v18, 0x1000, v18
	v_mov_b32_e32 v20, s53
	v_mov_b32_e32 v21, s49
	v_mov_b32_e32 v22, s52
	v_mov_b32_e32 v23, s48
	v_lshlrev_b32_e32 v24, 4, v19
	v_cmp_gt_u32_e32 vcc, s54, v19
	v_lshlrev_b32_e32 v25, 1, v18
	v_and_b32_e32 v82, 0x7f80, v24
	v_cndmask_b32_e32 v21, v20, v21, vcc
	v_cndmask_b32_e32 v20, v22, v23, vcc
	v_lshl_add_u64 v[20:21], v[20:21], 0, v[82:83]
	v_and_b32_e32 v82, 0x70, v25
	v_lshl_add_u64 v[20:21], v[20:21], 0, v[82:83]
	global_load_dwordx4 v[174:177], v[20:21], off
	v_lshrrev_b32_e32 v24, 3, v19
	v_mul_lo_u32 v24, v24, s56
	v_add3_u32 v181, 0, v24, v82
	v_add_u32_e32 v19, 0x200, v19
	v_add_u32_e32 v18, 0x1000, v18
	s_waitcnt vmcnt(0)
	ds_write_b128 v178, v[162:165]
	ds_write_b128 v179, v[166:169]
	ds_write_b128 v180, v[170:173]
	ds_write_b128 v181, v[174:177]
	s_nop 0
	s_nop 0
	s_nop 0
	s_nop 0
	s_nop 0
	s_nop 0
	s_nop 0
	s_nop 0
	s_nop 0
	s_nop 0
	s_nop 0
	s_nop 0
	s_nop 0
	s_nop 0
	s_nop 0
	s_nop 0
	s_nop 0
	s_nop 0
	s_nop 0
	s_nop 0
	s_nop 0
	s_nop 0
	s_nop 0
	s_nop 0
	s_nop 0
